# P1 RMSNorm row loop software-pipelined: next row's 8 loads issued (second 32-VGPR buffer) before the current row's reduce/rsqrt/store chain
# baseline (speedup 1.0000x reference)
; __device__ __forceinline__ void norm_phase(const float* X, const float* __restrict__ gain, const float* mod, int sh_off, int sc_off, bf16_t* H, int gw, int NGW, int lane) {
;     for (int rg = gw; rg < M / 8; rg += NGW) {
;         const int row0 = rg * 8, b = row0 >> 12;
;         f32x4 gs[8], sh[8];
; #pragma unroll
;         for (int j = 0; j < 8; ++j) { const f32x4 g = ((const f32x4*)gain)[lane + 64 * j]; const f32x4 s = ((const f32x4*)(mod + (size_t)b * NMOD + sc_off))[lane + 64 * j];
;             gs[j] = g * (s + 1.0f); sh[j] = ((const f32x4*)(mod + (size_t)b * NMOD + sh_off))[lane + 64 * j]; }
;         for (int r = 0; r < 8; ++r) {
;             const f32x4* xr = (const f32x4*)(X + (size_t)(row0 + r) * DM) + lane;
;             f32x4 v[8]; float ss = 0.f;
; #pragma unroll
;             for (int j = 0; j < 8; ++j) { v[j] = __builtin_nontemporal_load(xr + 64 * j); ss += (v[j].x * v[j].x + v[j].y * v[j].y) + (v[j].z * v[j].z + v[j].w * v[j].w); }
.LBB0_133:
	s_ashr_i32 s3, s2, 31
	s_lshl_b64 s[0:1], s[2:3], 13
	s_lshl_b64 s[6:7], s[2:3], 12
	s_ashr_i32 s3, s19, 9
	s_mul_hi_i32 s9, s3, 0xc000
	s_mul_i32 s3, s3, 0xc000
	s_add_u32 s8, s60, s3
	s_addc_u32 s9, s61, s9
	s_add_u32 s12, s8, 0x2000
	s_addc_u32 s13, s9, 0
	global_load_dwordx4 v[64:67], v142, s[12:13]
	global_load_dwordx4 v[68:71], v143, s[12:13]
	global_load_dwordx4 v[72:75], v144, s[12:13]
	global_load_dwordx4 v[76:79], v145, s[12:13]
	global_load_dwordx4 v[80:83], v146, s[12:13]
	global_load_dwordx4 v[84:87], v147, s[12:13]
	global_load_dwordx4 v[88:91], v148, s[12:13]
	global_load_dwordx4 v[92:95], v149, s[12:13]
	global_load_dwordx4 v[32:35], v142, s[8:9]
	global_load_dwordx4 v[36:39], v142, s[8:9] offset:1024
	global_load_dwordx4 v[40:43], v142, s[8:9] offset:2048
	global_load_dwordx4 v[44:47], v142, s[8:9] offset:3072
	global_load_dwordx4 v[48:51], v146, s[8:9]
	global_load_dwordx4 v[52:55], v147, s[8:9]
	global_load_dwordx4 v[56:59], v148, s[8:9]
	global_load_dwordx4 v[60:63], v149, s[8:9]
	v_lshl_add_u64 v[100:101], v[96:97], 0, s[0:1]
	v_lshl_add_u64 v[102:103], v[98:99], 0, s[6:7]
	s_mov_b64 s[6:7], 0
	s_waitcnt vmcnt(15)
	v_pk_add_f32 v[66:67], v[66:67], 1.0 op_sel_hi:[1,0]
	v_pk_add_f32 v[64:65], v[64:65], 1.0 op_sel_hi:[1,0]
	s_waitcnt vmcnt(14)
	v_pk_add_f32 v[70:71], v[70:71], 1.0 op_sel_hi:[1,0]
	v_pk_add_f32 v[68:69], v[68:69], 1.0 op_sel_hi:[1,0]
	s_waitcnt vmcnt(13)
	v_pk_add_f32 v[74:75], v[74:75], 1.0 op_sel_hi:[1,0]
	v_pk_add_f32 v[72:73], v[72:73], 1.0 op_sel_hi:[1,0]
	s_waitcnt vmcnt(12)
	v_pk_add_f32 v[78:79], v[78:79], 1.0 op_sel_hi:[1,0]
	v_pk_add_f32 v[76:77], v[76:77], 1.0 op_sel_hi:[1,0]
	s_waitcnt vmcnt(11)
	v_pk_add_f32 v[82:83], v[82:83], 1.0 op_sel_hi:[1,0]
	v_pk_add_f32 v[80:81], v[80:81], 1.0 op_sel_hi:[1,0]
	s_waitcnt vmcnt(10)
	v_pk_add_f32 v[86:87], v[86:87], 1.0 op_sel_hi:[1,0]
	v_pk_add_f32 v[84:85], v[84:85], 1.0 op_sel_hi:[1,0]
	s_waitcnt vmcnt(9)
	v_pk_add_f32 v[90:91], v[90:91], 1.0 op_sel_hi:[1,0]
	v_pk_add_f32 v[88:89], v[88:89], 1.0 op_sel_hi:[1,0]
	s_waitcnt vmcnt(8)
	v_pk_add_f32 v[94:95], v[94:95], 1.0 op_sel_hi:[1,0]
	v_pk_add_f32 v[92:93], v[92:93], 1.0 op_sel_hi:[1,0]
	v_pk_mul_f32 v[104:105], v[2:3], v[66:67]
	v_pk_mul_f32 v[106:107], v[0:1], v[64:65]
	v_pk_mul_f32 v[108:109], v[6:7], v[70:71]
	v_pk_mul_f32 v[110:111], v[4:5], v[68:69]
	v_pk_mul_f32 v[112:113], v[10:11], v[74:75]
	v_pk_mul_f32 v[114:115], v[8:9], v[72:73]
	v_pk_mul_f32 v[116:117], v[14:15], v[78:79]
	v_pk_mul_f32 v[118:119], v[12:13], v[76:77]
	v_pk_mul_f32 v[120:121], v[18:19], v[82:83]
	v_pk_mul_f32 v[122:123], v[16:17], v[80:81]
	v_pk_mul_f32 v[124:125], v[22:23], v[86:87]
	v_pk_mul_f32 v[126:127], v[20:21], v[84:85]
	v_pk_mul_f32 v[128:129], v[26:27], v[90:91]
	v_pk_mul_f32 v[130:131], v[24:25], v[88:89]
	v_pk_mul_f32 v[132:133], v[30:31], v[94:95]
	v_pk_mul_f32 v[134:135], v[28:29], v[92:93]
	global_load_dwordx4 v[196:199], v[100:101], off offset:-4096 nt
	global_load_dwordx4 v[192:195], v[100:101], off offset:-3072 nt
	global_load_dwordx4 v[200:203], v[100:101], off offset:-2048 nt
	global_load_dwordx4 v[204:207], v[100:101], off nt
	global_load_dwordx4 v[208:211], v[100:101], off offset:-1024 nt
	global_load_dwordx4 v[212:215], v[100:101], off offset:1024 nt
	global_load_dwordx4 v[216:219], v[100:101], off offset:3072 nt
	global_load_dwordx4 v[220:223], v[100:101], off offset:2048 nt
	v_lshl_add_u64 v[100:101], v[100:101], 0, s[4:5]
	s_waitcnt vmcnt(0)
	s_branch .Lp1_entry
.LBB0_134:
	s_waitcnt vmcnt(8)
.Lp1_entry:
	v_lshl_add_u64 v[152:153], v[102:103], 0, s[6:7]
	v_add_co_u32_e32 v152, vcc, s18, v152
	s_add_u32 s6, s6, 0x1000
	s_nop 0
	v_addc_co_u32_e32 v153, vcc, 0, v153, vcc
	s_addc_u32 s7, s7, 0
	s_cmpk_eq_u32 s6, 0x8000
	v_mov_b64_e32 v[64:65], v[192:193]
	v_mov_b64_e32 v[66:67], v[194:195]
	v_mov_b64_e32 v[68:69], v[196:197]
	v_mov_b64_e32 v[70:71], v[198:199]
	v_mov_b64_e32 v[72:73], v[200:201]
	v_mov_b64_e32 v[74:75], v[202:203]
	v_mov_b64_e32 v[76:77], v[204:205]
	v_mov_b64_e32 v[78:79], v[206:207]
	v_mov_b64_e32 v[80:81], v[208:209]
	v_mov_b64_e32 v[82:83], v[210:211]
	v_mov_b64_e32 v[84:85], v[212:213]
	v_mov_b64_e32 v[86:87], v[214:215]
	v_mov_b64_e32 v[88:89], v[216:217]
	v_mov_b64_e32 v[90:91], v[218:219]
	v_mov_b64_e32 v[92:93], v[220:221]
	v_mov_b64_e32 v[94:95], v[222:223]
	s_cbranch_scc1 .Lp1_nopf
	global_load_dwordx4 v[196:199], v[100:101], off offset:-4096 nt
	global_load_dwordx4 v[192:195], v[100:101], off offset:-3072 nt
	global_load_dwordx4 v[200:203], v[100:101], off offset:-2048 nt
	global_load_dwordx4 v[204:207], v[100:101], off nt
	global_load_dwordx4 v[208:211], v[100:101], off offset:-1024 nt
	global_load_dwordx4 v[212:215], v[100:101], off offset:1024 nt
	global_load_dwordx4 v[216:219], v[100:101], off offset:3072 nt
	global_load_dwordx4 v[220:223], v[100:101], off offset:2048 nt
	v_lshl_add_u64 v[100:101], v[100:101], 0, s[4:5]
; __device__ __forceinline__ unsigned cvt_pk_bf16(float lo, float hi) { unsigned r; asm volatile("v_cvt_pk_bf16_f32 %0, %1, %2" : "=v"(r) : "v"(lo), "v"(hi)); return r; }
; __device__ __forceinline__ void norm_phase(const float* X, const float* __restrict__ gain, const float* mod, int sh_off, int sc_off, bf16_t* H, int gw, int NGW, int lane) {
;     ...
;             const f32x4* xr = (const f32x4*)(X + (size_t)(row0 + r) * DM) + lane;
;             f32x4 v[8]; float ss = 0.f;
; #pragma unroll
;             for (int j = 0; j < 8; ++j) { v[j] = __builtin_nontemporal_load(xr + 64 * j); ss += (v[j].x * v[j].x + v[j].y * v[j].y) + (v[j].z * v[j].z + v[j].w * v[j].w); }
;             const float rstd = 1.0f / sqrtf(wave_sum(ss) * (1.0f / DM) + EPS);
;             u32x2* o8 = (u32x2*)(H + (size_t)(row0 + r) * DM) + lane;
; #pragma unroll
;             for (int j = 0; j < 8; ++j) { const f32x4 y = v[j] * rstd * gs[j] + sh[j]; u32x2 w; w.x = cvt_pk_bf16(y.x, y.y); w.y = cvt_pk_bf16(y.z, y.w); o8[64 * j] = w; }
.Lp1_nopf:
	v_mov_b32_e32 v156, v69
	v_mov_b32_e32 v157, v65
	v_mov_b32_e32 v162, v71
	v_mov_b32_e32 v163, v67
	v_mov_b32_e32 v154, v68
	v_mov_b32_e32 v155, v64
	v_mov_b32_e32 v158, v70
	v_mov_b32_e32 v159, v66
	v_pk_mul_f32 v[164:165], v[74:75], v[74:75]
	v_pk_mul_f32 v[166:167], v[72:73], v[72:73]
	v_pk_mul_f32 v[156:157], v[156:157], v[156:157]
	v_pk_mul_f32 v[162:163], v[162:163], v[162:163]
	v_pk_mov_b32 v[180:181], v[166:167], v[164:165] op_sel:[1,0]
	v_mov_b32_e32 v167, v165
	v_pk_fma_f32 v[154:155], v[154:155], v[154:155], v[156:157]
	v_pk_fma_f32 v[156:157], v[158:159], v[158:159], v[162:163]
	v_mul_f32_e32 v168, v81, v81
	v_mul_f32_e32 v170, v83, v83
	v_pk_add_f32 v[158:159], v[180:181], v[166:167]
	v_pk_add_f32 v[154:155], v[154:155], v[156:157]
	v_mul_f32_e32 v161, v76, v76
	v_mul_f32_e32 v179, v77, v77
	v_mul_f32_e32 v182, v78, v78
	v_mul_f32_e32 v183, v79, v79
	v_pk_fma_f32 v[164:165], v[80:81], v[80:81], v[168:169] op_sel_hi:[1,1,0]
	v_pk_fma_f32 v[168:169], v[82:83], v[82:83], v[170:171] op_sel_hi:[1,1,0]
	v_pk_add_f32 v[156:157], v[158:159], v[158:159] op_sel:[0,1] op_sel_hi:[1,0]
	v_pk_add_f32 v[154:155], v[154:155], v[154:155] op_sel:[0,1] op_sel_hi:[1,0]
	v_pk_mul_f32 v[172:173], v[86:87], v[86:87]
	v_pk_mul_f32 v[174:175], v[84:85], v[84:85]
	v_mov_b32_e32 v165, v182
	v_mov_b32_e32 v169, v183
	v_mov_b32_e32 v157, v179
	v_mov_b32_e32 v155, v161
	v_pk_mov_b32 v[170:171], v[174:175], v[172:173] op_sel:[1,0]
	v_mov_b32_e32 v175, v173
	v_pk_add_f32 v[158:159], v[164:165], v[168:169]
	v_pk_add_f32 v[154:155], v[154:155], v[156:157]
	v_mul_f32_e32 v176, v93, v93
	v_mul_f32_e32 v178, v95, v95
	v_pk_add_f32 v[162:163], v[170:171], v[174:175]
	v_pk_add_f32 v[154:155], v[154:155], v[158:159]
	v_mul_f32_e32 v184, v88, v88
	v_mul_f32_e32 v185, v89, v89
	v_mul_f32_e32 v188, v90, v90
	v_mul_f32_e32 v189, v91, v91
	v_pk_fma_f32 v[172:173], v[92:93], v[92:93], v[176:177] op_sel_hi:[1,1,0]
	v_pk_fma_f32 v[176:177], v[94:95], v[94:95], v[178:179] op_sel_hi:[1,1,0]
	v_pk_add_f32 v[162:163], v[162:163], v[162:163] op_sel:[0,1] op_sel_hi:[1,0]
	v_pk_add_f32 v[154:155], v[154:155], v[154:155] op_sel:[0,1] op_sel_hi:[1,0]
	v_mov_b32_e32 v173, v188
	v_mov_b32_e32 v177, v189
	v_mov_b32_e32 v163, v185
	v_mov_b32_e32 v155, v184
	v_pk_add_f32 v[164:165], v[172:173], v[176:177]
	v_pk_add_f32 v[154:155], v[154:155], v[162:163]
	s_nop 0
	v_pk_add_f32 v[154:155], v[154:155], v[164:165]
	s_nop 0
	v_add_f32_e32 v154, v154, v155
	ds_bpermute_b32 v155, v136, v154
	s_waitcnt lgkmcnt(0)
	v_add_f32_e32 v154, v154, v155
	ds_bpermute_b32 v155, v137, v154
	s_waitcnt lgkmcnt(0)
	v_add_f32_e32 v154, v154, v155
	ds_bpermute_b32 v155, v138, v154
	s_waitcnt lgkmcnt(0)
	v_add_f32_e32 v154, v154, v155
	ds_bpermute_b32 v155, v139, v154
	s_waitcnt lgkmcnt(0)
	v_add_f32_e32 v154, v154, v155
	ds_bpermute_b32 v155, v140, v154
	s_waitcnt lgkmcnt(0)
	v_add_f32_e32 v154, v154, v155
	ds_bpermute_b32 v155, v141, v154
	s_waitcnt lgkmcnt(0)
	v_add_f32_e32 v154, v154, v155
	v_fmamk_f32 v154, v154, 0x3a000000, v150
	v_mul_f32_e32 v155, 0x4f800000, v154
	v_cmp_gt_f32_e32 vcc, s17, v154
	s_nop 1
	v_cndmask_b32_e32 v154, v154, v155, vcc
	v_sqrt_f32_e32 v155, v154
	s_nop 0
	v_add_u32_e32 v156, -1, v155
	v_add_u32_e32 v157, 1, v155
	v_fma_f32 v158, -v156, v155, v154
	v_fma_f32 v159, -v157, v155, v154
	v_cmp_ge_f32_e64 s[0:1], 0, v158
	s_nop 1
	v_cndmask_b32_e64 v155, v155, v156, s[0:1]
	v_cmp_lt_f32_e64 s[0:1], 0, v159
	s_nop 1
	v_cndmask_b32_e64 v155, v155, v157, s[0:1]
	v_mul_f32_e32 v156, 0x37800000, v155
	v_cndmask_b32_e32 v155, v155, v156, vcc
	v_cmp_class_f32_e32 vcc, v154, v151
	s_nop 1
	v_cndmask_b32_e32 v154, v155, v154, vcc
	v_div_scale_f32 v155, s[0:1], v154, v154, 1.0
	v_rcp_f32_e32 v157, v155
	v_div_scale_f32 v156, vcc, 1.0, v154, 1.0
	v_fma_f32 v158, -v155, v157, 1.0
	v_fmac_f32_e32 v157, v158, v157
	v_mul_f32_e32 v158, v156, v157
	v_fma_f32 v159, -v155, v158, v156
	v_fmac_f32_e32 v158, v159, v157
	v_fma_f32 v155, -v155, v158, v156
	v_div_fmas_f32 v155, v155, v157, v158
	v_div_fixup_f32 v154, v155, v154, 1.0
	v_pk_mul_f32 v[68:69], v[68:69], v[154:155] op_sel_hi:[1,0]
	v_pk_mul_f32 v[64:65], v[64:65], v[154:155] op_sel_hi:[1,0]
	v_pk_mul_f32 v[70:71], v[70:71], v[154:155] op_sel_hi:[1,0]
	v_pk_mul_f32 v[66:67], v[66:67], v[154:155] op_sel_hi:[1,0]
	v_pk_fma_f32 v[68:69], v[106:107], v[68:69], v[32:33]
	v_pk_fma_f32 v[64:65], v[110:111], v[64:65], v[36:37]
	v_pk_mul_f32 v[72:73], v[72:73], v[154:155] op_sel_hi:[1,0]
	v_pk_mul_f32 v[74:75], v[74:75], v[154:155] op_sel_hi:[1,0]
	v_pk_fma_f32 v[70:71], v[104:105], v[70:71], v[34:35]
	v_pk_fma_f32 v[66:67], v[108:109], v[66:67], v[38:39]
	v_cvt_pk_bf16_f32 v68, v68, v69
	v_cvt_pk_bf16_f32 v69, v70, v71
	global_store_dwordx2 v[152:153], v[68:69], off
	v_cvt_pk_bf16_f32 v64, v64, v65
	v_cvt_pk_bf16_f32 v65, v66, v67
	v_pk_mul_f32 v[80:81], v[80:81], v[154:155] op_sel_hi:[1,0]
	v_pk_mul_f32 v[82:83], v[82:83], v[154:155] op_sel_hi:[1,0]
	v_pk_fma_f32 v[74:75], v[112:113], v[74:75], v[42:43]
	v_pk_fma_f32 v[72:73], v[114:115], v[72:73], v[40:41]
	global_store_dwordx2 v[152:153], v[64:65], off offset:512
	v_cvt_pk_bf16_f32 v64, v72, v73
	v_cvt_pk_bf16_f32 v65, v74, v75
	v_pk_mul_f32 v[76:77], v[76:77], v[154:155] op_sel_hi:[1,0]
	v_pk_mul_f32 v[78:79], v[78:79], v[154:155] op_sel_hi:[1,0]
	v_pk_fma_f32 v[82:83], v[116:117], v[82:83], v[46:47]
	v_pk_fma_f32 v[80:81], v[118:119], v[80:81], v[44:45]
	global_store_dwordx2 v[152:153], v[64:65], off offset:1024
	v_cvt_pk_bf16_f32 v64, v80, v81
	v_cvt_pk_bf16_f32 v65, v82, v83
	v_pk_mul_f32 v[84:85], v[84:85], v[154:155] op_sel_hi:[1,0]
	v_pk_mul_f32 v[86:87], v[86:87], v[154:155] op_sel_hi:[1,0]
	v_pk_fma_f32 v[78:79], v[120:121], v[78:79], v[50:51]
	v_pk_fma_f32 v[76:77], v[122:123], v[76:77], v[48:49]
	global_store_dwordx2 v[152:153], v[64:65], off offset:1536
	v_cvt_pk_bf16_f32 v64, v76, v77
	v_cvt_pk_bf16_f32 v65, v78, v79
	v_pk_mul_f32 v[92:93], v[92:93], v[154:155] op_sel_hi:[1,0]
	v_pk_mul_f32 v[94:95], v[94:95], v[154:155] op_sel_hi:[1,0]
	v_pk_fma_f32 v[86:87], v[124:125], v[86:87], v[54:55]
	v_pk_fma_f32 v[84:85], v[126:127], v[84:85], v[52:53]
	global_store_dwordx2 v[152:153], v[64:65], off offset:2048
	v_cvt_pk_bf16_f32 v64, v84, v85
	v_cvt_pk_bf16_f32 v65, v86, v87
	v_pk_mul_f32 v[88:89], v[88:89], v[154:155] op_sel_hi:[1,0]
	v_pk_mul_f32 v[90:91], v[90:91], v[154:155] op_sel_hi:[1,0]
	v_pk_fma_f32 v[94:95], v[128:129], v[94:95], v[58:59]
	v_pk_fma_f32 v[92:93], v[130:131], v[92:93], v[56:57]
	global_store_dwordx2 v[152:153], v[64:65], off offset:2560
	v_cvt_pk_bf16_f32 v64, v92, v93
	v_cvt_pk_bf16_f32 v65, v94, v95
	v_pk_fma_f32 v[90:91], v[132:133], v[90:91], v[62:63]
	v_pk_fma_f32 v[88:89], v[134:135], v[88:89], v[60:61]
	global_store_dwordx2 v[152:153], v[64:65], off offset:3072
	v_cvt_pk_bf16_f32 v64, v88, v89
	v_cvt_pk_bf16_f32 v65, v90, v91
	global_store_dwordx2 v[152:153], v[64:65], off offset:3584
	s_cbranch_scc0 .LBB0_134
; __device__ __forceinline__ void norm_phase(const float* X, const float* __restrict__ gain, const float* mod, int sh_off, int sc_off, bf16_t* H, int gw, int NGW, int lane) {
;     for (int rg = gw; rg < M / 8; rg += NGW) {
;         const int row0 = rg * 8, b = row0 >> 12;
	v_readlane_b32 s0, v236, 39
	s_add_i32 s19, s19, s0
	s_add_i32 s2, s2, s16
	s_cmpk_gt_i32 s19, 0x7ff
	v_readlane_b32 s1, v236, 40
	s_cbranch_scc0 .LBB0_133
